# speedup vs baseline: 1.0065x; 1.0011x over previous
.LBB0_56:
	s_sleep 1
	global_load_dword v0, v161, s[88:89] sc1
	s_waitcnt vmcnt(0)
	v_cmp_gt_u32_e32 vcc, s2, v0
	s_cbranch_vccnz .LBB0_56

.LBB0_397:
	s_sleep 1
	global_load_dword v0, v161, s[88:89] sc1
	s_waitcnt vmcnt(0)
	v_cmp_gt_u32_e32 vcc, s6, v0
	s_cbranch_vccnz .LBB0_397

.LBB0_888:
	s_sleep 1
	global_load_dword v0, v161, s[88:89] sc1
	s_waitcnt vmcnt(0)
	v_cmp_gt_u32_e32 vcc, s2, v0
	s_cbranch_vccnz .LBB0_888
	s_getpc_b64 s[98:99]
